# gather loop: one static s_setprio 1 for waves 0-3 (reset at loop exit)
# baseline (speedup 1.0000x reference)
.LBB0_975:
	s_or_b64 exec, exec, s[4:5]
	v_mov_b32_e32 v15, v202
	s_add_u32 s62, s28, 0x14000000
	s_waitcnt lgkmcnt(0)
	s_barrier
	s_nop 0
	s_nop 0
	s_nop 0
	s_nop 0
	s_nop 0
	s_nop 0
	s_nop 0
	s_nop 0
	s_nop 0
	s_nop 0
	s_nop 0
	s_nop 0
	s_addc_u32 s63, s29, 0
	v_readfirstlane_b32 s4, v15
	s_ashr_i32 s4, s4, 6
	s_and_b64 s[6:7], s[46:47], exec
	s_cselect_b32 s5, 8, 1
	v_cvt_f32_ubyte0_e32 v1, s5
	v_rcp_iflag_f32_e32 v1, v1
	s_add_i32 s8, s5, -1
	s_and_b64 s[6:7], s[46:47], exec
	s_cselect_b32 s24, 3, 0
	v_mul_f32_e32 v1, 0x4f7ffffe, v1
	v_cvt_u32_f32_e32 v1, v1
	s_sub_i32 s9, 0, s5
	s_abs_i32 s7, s30
	s_lshr_b32 s6, s2, s24
	v_readfirstlane_b32 s10, v1
	s_mul_i32 s9, s9, s10
	s_mul_hi_u32 s9, s10, s9
	s_add_i32 s10, s10, s9
	s_mul_hi_u32 s9, s7, s10
	s_mul_i32 s10, s9, s5
	s_sub_i32 s7, s7, s10
	s_lshl_b32 s6, s6, 3
	s_ashr_i32 s68, s30, 31
	s_add_i32 s10, s9, 1
	s_sub_i32 s11, s7, s5
	s_cmp_ge_u32 s7, s5
	s_cselect_b32 s9, s10, s9
	s_cselect_b32 s7, s11, s7
	s_add_i32 s10, s9, 1
	s_cmp_ge_u32 s7, s5
	s_cselect_b32 s7, s10, s9
	s_xor_b32 s7, s7, s68
	s_sub_i32 s7, s7, s68
	s_lshl_b32 s25, s7, 3
	s_abs_i32 s7, s25
	v_cvt_f32_u32_e32 v1, s7
	s_add_i32 s40, s4, s6
	s_sub_i32 s6, s25, s40
	s_and_b32 s41, s8, s2
	v_rcp_iflag_f32_e32 v1, v1
	s_add_i32 s8, s6, 0x1fff
	s_sub_i32 s6, 0xffffe001, s6
	s_xor_b32 s9, s8, s25
	v_mul_f32_e32 v1, 0x4f7ffffe, v1
	v_cvt_u32_f32_e32 v1, v1
	s_max_i32 s6, s8, s6
	s_sub_i32 s8, 0, s7
	s_ashr_i32 s9, s9, 31
	v_readfirstlane_b32 s10, v1
	s_mul_i32 s8, s8, s10
	s_mul_hi_u32 s8, s10, s8
	s_add_i32 s10, s10, s8
	s_mul_hi_u32 s8, s6, s10
	s_mul_i32 s10, s8, s7
	s_sub_i32 s6, s6, s10
	s_add_i32 s10, s8, 1
	s_sub_i32 s11, s6, s7
	s_cmp_ge_u32 s6, s7
	s_cselect_b32 s8, s10, s8
	s_cselect_b32 s6, s11, s6
	s_add_i32 s10, s8, 1
	s_cmp_ge_u32 s6, s7
	s_cselect_b32 s6, s10, s8
	s_sub_i32 s5, s5, s41
	s_xor_b32 s6, s6, s9
	s_add_i32 s5, s5, 15
	s_sub_i32 s42, s6, s9
	s_lshr_b32 s5, s5, s24
	s_mul_i32 s43, s42, s5
	s_cmp_lt_i32 s43, 1
	s_mov_b32 s9, 0
	s_cbranch_scc1 .LBB0_980
	s_lshl_b32 s5, s4, 14
	s_lshl_b32 s4, s4, 10
	s_add_i32 s47, s4, 0
	s_lshr_b32 s8, s41, 2
	s_add_i32 s46, s5, 0
	s_add_i32 s47, s47, 0x20000
	s_and_b32 s10, s41, 3
	s_lshl_b64 s[4:5], s[8:9], 13
	s_ashr_i32 s6, s40, 31
	s_add_u32 s4, s4, s40
	s_addc_u32 s5, s5, s6
	s_lshl_b64 s[6:7], s[4:5], 9
	v_and_b32_e32 v14, 63, v15
	s_add_u32 s6, s44, s6
	s_addc_u32 s7, s45, s7
	v_lshlrev_b32_e32 v42, 3, v14
	global_load_dwordx2 v[2:3], v42, s[6:7]
	v_and_b32_e32 v17, 15, v15
	v_bfe_u32 v4, v15, 4, 2
	v_bfe_u32 v6, v15, 2, 2
	v_and_b32_e32 v1, 7, v15
	v_lshlrev_b32_e32 v34, 3, v15
	v_mov_b32_e32 v7, 0x1000
	v_lshrrev_b32_e32 v9, 3, v15
	v_or_b32_e32 v12, 16, v17
	v_lshl_or_b32 v6, v4, 2, v6
	v_bfe_u32 v5, v15, 3, 1
	v_and_b32_e32 v10, 1, v15
	v_bitop3_b32 v13, v4, v1, 4 bitop3:0x36
	v_bitop3_b32 v16, v4, v15, 7 bitop3:0x78
	v_and_or_b32 v7, v34, 24, v7
	v_xor_b32_e32 v9, v9, v15
	v_mul_u32_u24_e32 v21, 0x40004, v14
	v_lshrrev_b32_e32 v22, 3, v12
	v_lshlrev_b32_e32 v24, 4, v6
	v_lshlrev_b32_e32 v6, 7, v6
	s_cmpk_gt_i32 s40, 0xff
	s_movk_i32 s6, 0x60
	v_lshlrev_b32_e32 v12, 7, v12
	v_xor_b32_e32 v23, v13, v5
	v_xor_b32_e32 v5, v16, v5
	v_and_or_b32 v9, v9, 6, v10
	v_or_b32_e32 v60, 0x10000, v21
	v_or_b32_e32 v61, 0x30002, v21
	v_xor_b32_e32 v10, v13, v22
	v_xor_b32_e32 v13, v16, v22
	v_or_b32_e32 v16, 0x800, v6
	v_or_b32_e32 v6, v6, v7
	s_cselect_b64 vcc, -1, 0
	v_lshlrev_b32_e32 v11, 6, v15
	s_waitcnt vmcnt(2)
	v_lshlrev_b32_e32 v52, 4, v9
	v_add_u32_e32 v9, s47, v42
	v_lshl_or_b32 v37, v10, 4, v12
	v_bitop3_b32 v10, v24, v16, s6 bitop3:0xce
	v_bitop3_b32 v39, v24, v6, s6 bitop3:0xce
	s_mul_hi_u32 s6, s4, 0x1200
	s_mulk_i32 s5, 0x1200
	s_mulk_i32 s4, 0x1200
	s_add_i32 s6, s6, s5
	v_mov_b32_e32 v43, 0
	s_add_u32 s4, s38, s4
	v_mov_b32_e32 v8, 0x60
	v_lshlrev_b32_e32 v19, 7, v17
	s_addc_u32 s5, s39, s6
	v_lshl_or_b32 v35, v23, 4, v19
	v_lshl_or_b32 v36, v5, 4, v19
	v_and_b32_e32 v5, 0x60, v24
	v_bitop3_b32 v19, v24, 64, v8 bitop3:0x6c
	v_bitop3_b32 v8, v24, 32, v8 bitop3:0x6c
	v_bfe_u32 v18, v15, 3, 3
	v_lshl_or_b32 v38, v13, 4, v12
	v_or_b32_e32 v12, v19, v16
	v_or_b32_e32 v13, v8, v16
	v_or_b32_e32 v41, v8, v6
	v_or_b32_e32 v8, v5, v16
	s_waitcnt vmcnt(1)
	v_or_b32_e32 v56, v6, v5
	v_lshlrev_b32_e32 v16, 3, v4
	v_and_b32_e32 v4, 48, v15
	v_mov_b32_e32 v5, v43
	v_lshlrev_b32_e32 v63, 6, v18
	v_bitop3_b32 v20, v18, v15, 7 bitop3:0x78
	v_or_b32_e32 v40, v19, v6
	v_add_u32_e32 v57, v10, v7
	v_add_u32_e32 v58, v12, v7
	v_add_u32_e32 v59, v13, v7
	v_add_u32_e32 v90, v8, v7
	v_add_u32_e32 v18, s47, v63
	v_mov_b32_e32 v19, v43
	v_lshlrev_b32_e32 v44, 4, v20
	v_mov_b32_e32 v45, v43
	s_mov_b32 m0, s46
	v_mov_b32_e32 v53, v43
	v_mov_b32_e32 v64, 9
	v_xor_b32_e32 v50, 16, v44
	v_mov_b32_e32 v51, v43
	v_xor_b32_e32 v48, 32, v44
	s_waitcnt vmcnt(0)
	v_cndmask_b32_e32 v2, v60, v2, vcc
	v_cndmask_b32_e32 v3, v61, v3, vcc
	ds_write_b64 v9, v[2:3]
	v_and_b32_e32 v2, 0xc0, v11
	v_lshlrev_b32_e32 v62, 1, v2
	v_lshl_or_b32 v2, s10, 9, v62
	v_mov_b32_e32 v3, v43
	v_lshl_add_u64 v[2:3], s[4:5], 0, v[2:3]
	s_lshl_b64 s[4:5], s[8:9], 22
	s_add_u32 s6, s80, s4
	v_lshl_add_u64 v[2:3], v[2:3], 0, v[4:5]
	s_addc_u32 s7, s81, s5
	global_load_dwordx4 v[10:13], v[2:3], off
	global_load_dwordx4 v[6:9], v[2:3], off offset:64
	s_waitcnt lgkmcnt(0)
	s_add_u32 s4, s37, s4
	ds_read_b128 v[30:33], v18
	ds_read_b128 v[22:25], v18 offset:16
	ds_read_b128 v[2:5], v18 offset:32
	ds_read_b128 v[26:29], v18 offset:48
	s_addc_u32 s5, s79, s5
	s_lshl_b32 s8, s10, 7
	s_add_u32 s4, s4, s8
	s_addc_u32 s5, s5, 0
	s_waitcnt lgkmcnt(3)
	v_lshlrev_b32_e32 v18, 9, v30
	s_add_u32 s6, s6, s8
	v_and_b32_e32 v18, 0x1fffe00, v18
	s_addc_u32 s7, s7, 0
	v_lshl_add_u64 v[20:21], s[4:5], 0, v[18:19]
	s_add_i32 s48, s46, 0x1000
	v_lshl_add_u64 v[20:21], v[20:21], 0, v[44:45]
	v_lshl_add_u64 v[18:19], s[6:7], 0, v[18:19]
	global_load_lds_dwordx4 v[20:21], off
	v_lshl_add_u64 v[18:19], v[18:19], 0, v[52:53]
	s_mov_b32 m0, s48
	s_add_i32 s49, s46, 0x400
	global_load_lds_dwordx4 v[18:19], off
	v_lshlrev_b32_sdwa v18, v64, v30 dst_sel:DWORD dst_unused:UNUSED_PAD src0_sel:DWORD src1_sel:WORD_1
	v_mov_b32_e32 v19, v43
	v_lshl_add_u64 v[20:21], s[4:5], 0, v[18:19]
	v_lshl_add_u64 v[20:21], v[20:21], 0, v[50:51]
	s_mov_b32 m0, s49
	v_lshl_add_u64 v[18:19], s[6:7], 0, v[18:19]
	s_add_i32 s50, s46, 0x1400
	global_load_lds_dwordx4 v[20:21], off
	v_lshl_add_u64 v[18:19], v[18:19], 0, v[52:53]
	s_mov_b32 m0, s50
	v_mov_b32_e32 v49, v43
	global_load_lds_dwordx4 v[18:19], off
	v_lshlrev_b32_e32 v18, 9, v31
	v_and_b32_e32 v18, 0x1fffe00, v18
	v_mov_b32_e32 v19, v43
	v_lshl_add_u64 v[20:21], s[4:5], 0, v[18:19]
	s_add_i32 s51, s46, 0x800
	v_lshl_add_u64 v[20:21], v[20:21], 0, v[48:49]
	s_mov_b32 m0, s51
	v_lshl_add_u64 v[18:19], s[6:7], 0, v[18:19]
	s_add_i32 s52, s46, 0x1800
	global_load_lds_dwordx4 v[20:21], off
	v_lshl_add_u64 v[18:19], v[18:19], 0, v[52:53]
	s_mov_b32 m0, s52
	v_xor_b32_e32 v46, 48, v44
	global_load_lds_dwordx4 v[18:19], off
	v_lshlrev_b32_sdwa v18, v64, v31 dst_sel:DWORD dst_unused:UNUSED_PAD src0_sel:DWORD src1_sel:WORD_1
	v_mov_b32_e32 v19, v43
	v_lshl_add_u64 v[20:21], s[4:5], 0, v[18:19]
	v_mov_b32_e32 v47, v43
	s_add_i32 s53, s46, 0xc00
	v_lshl_add_u64 v[20:21], v[20:21], 0, v[46:47]
	s_mov_b32 m0, s53
	v_lshl_add_u64 v[18:19], s[6:7], 0, v[18:19]
	s_add_i32 s54, s46, 0x1c00
	global_load_lds_dwordx4 v[20:21], off
	v_lshl_add_u64 v[18:19], v[18:19], 0, v[52:53]
	s_mov_b32 m0, s54
	v_cmp_gt_u32_e64 s[4:5], 4, v17
	global_load_lds_dwordx4 v[18:19], off
	v_and_b32_e32 v17, 0x80, v34
	v_bfe_u32 v15, v15, 5, 1
	v_or_b32_e32 v19, 32, v17
	v_or_b32_e32 v20, 64, v17
	v_or_b32_e32 v21, 0x60, v17
	v_or_b32_e32 v30, 6, v15
	v_or_b32_e32 v82, v17, v30
	v_or_b32_e32 v84, v19, v30
	v_or_b32_e32 v86, v20, v30
	v_or_b32_e32 v88, v21, v30
	v_or_b32_e32 v30, 10, v15
	v_or_b32_e32 v18, 2, v15
	v_or_b32_e32 v98, v17, v30
	v_or_b32_e32 v100, v19, v30
	v_or_b32_e32 v102, v20, v30
	v_or_b32_e32 v104, v21, v30
	v_or_b32_e32 v30, 14, v15
	v_or_b32_e32 v66, v17, v18
	v_or_b32_e32 v68, v19, v18
	v_or_b32_e32 v70, v20, v18
	v_or_b32_e32 v72, v21, v18
	v_or_b32_e32 v18, 4, v15
	v_or_b32_e32 v106, v17, v30
	v_or_b32_e32 v108, v19, v30
	v_or_b32_e32 v110, v20, v30
	v_or_b32_e32 v112, v21, v30
	v_or_b32_e32 v30, 18, v15
	v_or_b32_e32 v81, v17, v18
	v_or_b32_e32 v83, v19, v18
	v_or_b32_e32 v85, v20, v18
	v_or_b32_e32 v87, v21, v18
	v_or_b32_e32 v18, 8, v15
	v_or_b32_e32 v114, v17, v30
	v_or_b32_e32 v116, v19, v30
	v_or_b32_e32 v118, v20, v30
	v_or_b32_e32 v120, v21, v30
	v_or_b32_e32 v30, 22, v15
	v_lshl_add_u64 v[54:55], s[44:45], 0, v[42:43]
	v_or_b32_e32 v97, v17, v18
	v_or_b32_e32 v99, v19, v18
	v_or_b32_e32 v101, v20, v18
	v_or_b32_e32 v103, v21, v18
	v_or_b32_e32 v18, 12, v15
	v_or_b32_e32 v122, v17, v30
	v_or_b32_e32 v124, v19, v30
	v_or_b32_e32 v126, v20, v30
	v_or_b32_e32 v128, v21, v30
	v_or_b32_e32 v30, 26, v15
	s_abs_i32 s45, s42
	v_or_b32_e32 v105, v17, v18
	v_or_b32_e32 v107, v19, v18
	v_or_b32_e32 v109, v20, v18
	v_or_b32_e32 v111, v21, v18
	v_or_b32_e32 v18, 16, v15
	v_or_b32_e32 v130, v17, v30
	v_or_b32_e32 v132, v19, v30
	v_or_b32_e32 v134, v20, v30
	v_or_b32_e32 v136, v21, v30
	v_cvt_f32_u32_e32 v30, s45
	v_or_b32_e32 v113, v17, v18
	v_or_b32_e32 v115, v19, v18
	v_or_b32_e32 v117, v20, v18
	v_or_b32_e32 v119, v21, v18
	v_or_b32_e32 v18, 20, v15
	v_or_b32_e32 v121, v17, v18
	v_or_b32_e32 v123, v19, v18
	v_or_b32_e32 v125, v20, v18
	v_or_b32_e32 v127, v21, v18
	v_or_b32_e32 v18, 24, v15
	v_or_b32_e32 v65, v17, v15
	v_or_b32_e32 v67, v19, v15
	v_or_b32_e32 v69, v20, v15
	v_or_b32_e32 v71, v21, v15
	v_or_b32_e32 v129, v17, v18
	v_or_b32_e32 v131, v19, v18
	v_or_b32_e32 v133, v20, v18
	v_or_b32_e32 v135, v21, v18
	v_or_b32_e32 v18, 28, v15
	v_or_b32_e32 v15, 30, v15
	v_or_b32_e32 v137, v17, v18
	v_or_b32_e32 v138, v17, v15
	v_rcp_iflag_f32_e32 v17, v30
	s_sub_i32 s8, 0, s45
	s_add_i32 s44, s46, 0x2000
	v_lshlrev_b32_e32 v1, 2, v14
	v_mul_f32_e32 v17, 0x4f7ffffe, v17
	v_cvt_u32_f32_e32 v17, v17
	s_waitcnt vmcnt(0)
	v_cndmask_b32_e64 v9, 0, v9, s[4:5]
	v_cndmask_b32_e64 v8, 0, v8, s[4:5]
	v_cndmask_b32_e64 v7, 0, v7, s[4:5]
	v_readfirstlane_b32 s10, v17
	s_mul_i32 s8, s8, s10
	s_mul_hi_u32 s8, s10, s8
	v_cndmask_b32_e64 v6, 0, v6, s[4:5]
	v_cndmask_b32_e64 v13, 0, v13, s[4:5]
	v_cndmask_b32_e64 v12, 0, v12, s[4:5]
	v_cndmask_b32_e64 v11, 0, v11, s[4:5]
	v_cndmask_b32_e64 v10, 0, v10, s[4:5]
	v_cmp_gt_u32_e64 s[6:7], 16, v14
	v_add_u32_e32 v73, s46, v56
	v_add_u32_e32 v74, s46, v90
	v_add_u32_e32 v75, s46, v41
	v_add_u32_e32 v76, s46, v59
	v_add_u32_e32 v77, s46, v40
	v_add_u32_e32 v78, s46, v58
	v_add_u32_e32 v79, s46, v39
	v_add_u32_e32 v80, s46, v57
	v_add_u32_e32 v89, s44, v56
	v_add_u32_e32 v90, s44, v90
	v_add_u32_e32 v91, s44, v41
	v_add_u32_e32 v92, s44, v59
	v_add_u32_e32 v93, s44, v40
	v_add_u32_e32 v94, s44, v58
	v_add_u32_e32 v95, s44, v39
	v_add_u32_e32 v96, s44, v57
	v_or_b32_e32 v139, v19, v18
	v_or_b32_e32 v140, v19, v15
	v_or_b32_e32 v141, v20, v18
	v_or_b32_e32 v142, v20, v15
	v_or_b32_e32 v143, v21, v18
	v_or_b32_e32 v144, v21, v15
	s_ashr_i32 s55, s42, 31
	s_add_i32 s56, s10, s8
	s_sub_i32 s57, 0, s42
	v_lshlrev_b32_e32 v56, 1, v16
	s_add_i32 s58, s46, 0x3000
	s_add_i32 s59, s46, 0x2400
	s_add_i32 s60, s46, 0x3400
	s_add_i32 s61, s46, 0x2800
	s_add_i32 s64, s46, 0x3800
	s_add_i32 s65, s46, 0x2c00
	s_add_i32 s66, s46, 0x3c00
	v_add_u32_e32 v145, s46, v36
	v_add_u32_e32 v149, s46, v35
	v_add_u32_e32 v151, s46, v38
	v_add_u32_e32 v153, s46, v37
	v_lshlrev_b32_e32 v58, 1, v14
	s_movk_i32 s67, 0x7fff
	s_mov_b32 s69, 0
	s_mov_b32 s70, 0
	v_readfirstlane_b32 s12, v202
	s_lshr_b32 s12, s12, 6
	s_cmp_ge_u32 s12, 4
	s_cbranch_scc1 .Lg_prio_done
	s_setprio 1
.Lg_prio_done:
	s_branch .LBB0_978

.LBB0_980:
	s_setprio 0
	s_waitcnt vmcnt(0)
	s_waitcnt vmcnt(0) lgkmcnt(0)
	s_barrier
	s_and_saveexec_b64 s[4:5], s[20:21]
	s_cbranch_execz .LBB0_1032
	s_add_i32 s6, 0, 0x25e00
	v_mov_b32_e32 v1, s6
	s_waitcnt vmcnt(0) expcnt(0) lgkmcnt(0)
	ds_read_b32 v3, v1
	s_add_i32 s6, 0, 0x25e04
	v_mov_b32_e32 v1, s6
	ds_read_b32 v1, v1
	s_waitcnt lgkmcnt(1)
	v_cmp_ne_u32_e32 vcc, 0, v3
	s_cbranch_vccnz .LBB0_996
	s_load_dword s6, s[26:27], 0x14
	s_mov_b32 s37, 1
	v_mov_b32_e32 v17, 0
	s_waitcnt lgkmcnt(0)
	s_lshr_b32 s8, s6, 16
	s_and_b32 s6, s6, 0xffff
	s_cmp_lg_u32 s6, 0
	s_cselect_b64 s[6:7], -1, 0
	s_cmp_lg_u64 s[6:7], 0
	s_addc_u32 s6, s31, 0
	s_cmp_lg_u32 s8, 0
	s_mul_i32 s64, s6, s30
	s_cselect_b64 s[6:7], -1, 0
	s_cmp_lg_u64 s[6:7], 0
	s_addc_u32 s6, s96, 0
	s_mul_i32 s64, s64, s6
	s_add_u32 s6, s28, 0x3c00200
	s_addc_u32 s7, s29, 0
	s_add_u32 s8, s28, 0x3c00400
	s_addc_u32 s9, s29, 0
	s_add_u32 s10, s28, 0x3c00500
	s_addc_u32 s11, s29, 0
	s_add_u32 s12, s28, 0x3c00600
	s_addc_u32 s13, s29, 0
	s_add_u32 s14, s28, 0x3c00700
	s_addc_u32 s15, s29, 0
	s_add_u32 s16, s28, 0x3c00800
	s_addc_u32 s17, s29, 0
	s_add_u32 s18, s28, 0x3c00900
	s_addc_u32 s19, s29, 0
	s_add_u32 s22, s28, 0x3c00a00
	s_addc_u32 s23, s29, 0
	s_add_u32 s24, s28, 0x3c00b00
	s_addc_u32 s25, s29, 0
	s_add_u32 s40, s28, 0x3c00c00
	s_addc_u32 s41, s29, 0
	s_add_u32 s42, s28, 0x3c00d00
	s_addc_u32 s43, s29, 0
	s_add_u32 s44, s28, 0x3c00e00
	s_addc_u32 s45, s29, 0
	s_add_u32 s46, s28, 0x3c00f00
	s_addc_u32 s47, s29, 0
	s_add_u32 s48, s28, 0x3c01000
	s_addc_u32 s49, s29, 0
	s_add_u32 s50, s28, 0x3c01100
	s_addc_u32 s51, s29, 0
	s_add_u32 s52, s28, 0x3c01200
	s_addc_u32 s53, s29, 0
	s_add_u32 s54, s28, 0x3c01300
	s_addc_u32 s55, s29, 0
	s_branch .LBB0_984

.LBB0_1032:
	s_or_b64 exec, exec, s[4:5]
	s_add_u32 s12, s28, 0x1c000000
	s_addc_u32 s13, s29, 0
	s_waitcnt lgkmcnt(0)
	v_lshlrev_b32_e32 v1, 1, v212
	s_cmpk_lt_i32 s2, 0x200
	v_readfirstlane_b32 s16, v202
	s_cselect_b64 s[6:7], -1, 0
	s_cmpk_gt_i32 s2, 0x1ff
	v_bitop3_b32 v178, v1, v161, v159 bitop3:0x36
	s_barrier
	s_nop 0
	s_nop 0
	s_nop 0
	s_nop 0
	s_nop 0
	s_nop 0
	s_nop 0
	s_nop 0
	s_nop 0
	s_nop 0
	s_nop 0
	s_nop 0
	s_nop 0
	s_nop 0
	s_nop 0
	s_nop 0
	s_nop 0
	s_nop 0
	s_nop 0
	s_nop 0
	s_nop 0
	s_nop 0
	s_nop 0
	s_nop 0
	s_nop 0
	s_nop 0
	s_nop 0
	s_nop 0
	s_nop 0
	s_nop 0
	s_nop 0
	s_nop 0
	s_nop 0
	s_nop 0
	s_nop 0
	s_nop 0
	s_nop 0
	s_nop 0
	s_nop 0
	s_nop 0
	s_nop 0
	s_nop 0
	s_nop 0
	s_nop 0
	s_nop 0
	s_nop 0
	s_nop 0
	s_nop 0
	s_nop 0
	s_nop 0
	s_nop 0
	s_nop 0
	s_nop 0
	s_nop 0
	s_nop 0
	s_nop 0
	s_nop 0
	s_nop 0
	s_cbranch_scc1 .LBB0_1056
	s_ashr_i32 s37, s2, 31
	s_lshr_b32 s4, s37, 29
	s_add_i32 s8, s2, s4
	s_and_b32 s4, s8, -8
	s_sub_i32 s10, s2, s4
	s_cmp_gt_i32 s10, -1
	s_cbranch_scc0 .LBB0_1035
	s_lshl_b32 s9, s10, 6
	s_cbranch_execz .LBB0_1036
	s_branch .LBB0_1037
